# attn LDS waits to first consumer + scalar row-sum; phase1 parity reorder; kv unit rotation; S5 Toeplitz ring prefetch + table staging batch
# speedup vs baseline: 1.0146x; 1.0146x over previous
; #define LAS __attribute__((address_space(3)))
; __global__ void __launch_bounds__(NWAVES * 64, 2) mk_fwd(Args args) {
;     extern __shared__ __attribute__((aligned(16))) unsigned char lds[];
;     Frame F;
;     F.lds = (LAS unsigned char*)lds;
;     F.tid = threadIdx.x; F.lane = F.tid & 63; F.wave = __builtin_amdgcn_readfirstlane(F.tid >> 6);
;     F.G = gridDim.x; { const int bx = blockIdx.x; F.vcu = (F.G % 8 == 0) ? (bx % 8) * (F.G / 8) + bx / 8 : bx; }
_Z6mk_fwd4Args:
	s_mov_b32 s98, 0
	s_load_dword s94, s[0:1], 0x110
	s_mov_b32 s97, s2
	v_readfirstlane_b32 s2, v0
	s_mov_b32 s77, s97
	s_nop 0
	v_writelane_b32 v254, s2, 0
	s_add_u32 s2, s0, 0x110
	s_addc_u32 s3, s1, 0
	v_writelane_b32 v254, s2, 1
	s_nop 1
	v_writelane_b32 v254, s3, 2
	s_waitcnt lgkmcnt(0)
	s_and_b32 s2, s94, 7
	s_cmp_lg_u32 s2, 0
	s_cbranch_scc1 .LBB0_2
	s_ashr_i32 s3, s97, 31
	s_lshr_b32 s3, s3, 29
	s_add_i32 s3, s97, s3
	s_and_b32 s4, s3, -8
	s_ashr_i32 s2, s94, 3
	s_sub_i32 s4, s97, s4
	s_mul_i32 s2, s2, s4
	s_ashr_i32 s3, s3, 3
	s_add_i32 s77, s2, s3

; #define PHASE(...) do { if (IN(pk)) { __VA_ARGS__ } if (REPEAT_PHASE == pk && IN(pk)) { { XcdBarrier bar_; bar_.bar = (unsigned*)ws_(F) + CW_BAR; bar_.x = xb_xcc_id(); bar_.st = (volatile LAS unsigned*)(F.lds + MISC_OFF) + 8; xcd_barrier(bar_); } asm volatile("" : "+v"(F.tid), "+v"(F.lane)); { __VA_ARGS__ } } SEAM(pk); ++pk; } while (0)
; __global__ void __launch_bounds__(NWAVES * 64, 2) mk_fwd(Args args) {
;     ...
;     PHASE( p0_prologue(F); p0_s5_tables(F); ph_init_rows(F); );
.LBB0_111:
	s_and_b32 s98, s97, 1
	s_cmp_eq_u32 s98, 1
	s_cbranch_scc0 .Lp1_tables
	s_waitcnt vmcnt(0) lgkmcnt(0)
	s_branch .Lp1_rows_entry

; #define GAS __attribute__((address_space(1)))
; __device__ __forceinline__ const float* xin_row(const Frame& F, int m) { return m < TL ? inp(F, 0) + (size_t)m * D : inp(F, 2) + (size_t)(m - TL) * D; }
; __device__ __forceinline__ const float* modvec(const Frame& F, int layer, int mr, int part) { return (const float*)(ws_(F) + WS_MOD) + (size_t)(layer * 3 + mr) * 6144 + part * 1024; }
; __device__ __forceinline__ void ph_init_rows(Frame& F) {
;     const int gw = F.vcu * NWAVES + F.wave, NGW = F.G * NWAVES;
;     constexpr int NR = 3;
;     for (int m0 = gw; m0 < TT; m0 += NR * NGW) {
;         f32x4 v[NR][4], sh[NR][4], sc[NR][4];
; #pragma unroll
;         for (int i = 0; i < NR; ++i) { const int mi = m0 + i * NGW, m = mi < TT ? mi : m0, mr = modrow_of(m);
;             const GAS f32x4* xr = (const GAS f32x4*)xin_row(F, m) + F.lane;
;             const GAS f32x4* shp = (const GAS f32x4*)modvec(F, 0, mr, 0) + F.lane; const GAS f32x4* scp = (const GAS f32x4*)modvec(F, 0, mr, 1) + F.lane;
; __device__ __forceinline__ void p0_s5_tables(Frame& F) {
;     ...
;     __syncthreads();
.LBB0_148:
	s_barrier
	s_cmp_eq_u32 s98, 2
	s_cbranch_scc1 .Lp1_done
.Lp1_rows_entry:
	s_cmpk_gt_i32 s18, 0x41ff
	s_cbranch_scc1 .LBB0_190
	s_add_i32 s0, 0, 0x204f8
	v_mov_b32_e32 v1, s0
	ds_read_b64 v[146:147], v1
	v_readlane_b32 s8, v254, 5
	s_ashr_i32 s19, s18, 31
	s_lshl_b32 s0, s77, 13
	s_lshl_b32 s1, s8, 10
	s_mul_i32 s2, s94, 24
	v_ashrrev_i32_e32 v235, 31, v234
	s_add_i32 s4, s0, s1
	s_lshl_b64 s[0:1], s[18:19], 11
	s_ashr_i32 s3, s2, 31
	v_readlane_b32 s9, v254, 6
	v_lshl_add_u64 v[2:3], v[234:235], 3, s[0:1]
	s_mov_b64 s[0:1], 0x1f00600
	s_mov_b32 s5, 0
	s_add_i32 s6, s18, 0xffffc000
	s_mul_i32 s15, s94, 0x6000
	v_lshl_add_u64 v[148:149], v[2:3], 0, s[0:1]
	s_lshl_b64 s[8:9], s[2:3], 11
	s_lshl_b32 s16, s94, 4
	s_lshl_b32 s17, s94, 14
	s_lshl_b32 s38, s94, 13
	s_add_i32 s39, 0, 0x20410
	s_add_i32 s40, 0, 0x20400
	v_lshlrev_b64 v[150:151], 4, v[234:235]
	s_mov_b64 s[10:11], 0x100000
	s_mov_b64 s[12:13], 0x101000
	s_mov_b32 s41, 0x101000
	s_mov_b32 s14, 0x3fb504f3
	s_mov_b64 s[20:21], 0x1f00000
	s_branch .LBB0_152

; #define PHASE(...) do { if (IN(pk)) { __VA_ARGS__ } if (REPEAT_PHASE == pk && IN(pk)) { { XcdBarrier bar_; bar_.bar = (unsigned*)ws_(F) + CW_BAR; bar_.x = xb_xcc_id(); bar_.st = (volatile LAS unsigned*)(F.lds + MISC_OFF) + 8; xcd_barrier(bar_); } asm volatile("" : "+v"(F.tid), "+v"(F.lane)); { __VA_ARGS__ } } SEAM(pk); ++pk; } while (0)
; __device__ __forceinline__ void ph_init_rows(Frame& F) {
;     ...
;     for (int m0 = gw; m0 < TT; m0 += NR * NGW) {
; __global__ void __launch_bounds__(NWAVES * 64, 2) mk_fwd(Args args) {
;     ...
;     PHASE( p0_prologue(F); p0_s5_tables(F); ph_init_rows(F); );
.LBB0_190:
	s_cmp_eq_u32 s98, 1
	s_cbranch_scc0 .Lp1_done
	s_mov_b32 s98, 2
	s_waitcnt vmcnt(0) lgkmcnt(0)
	s_branch .Lp1_tables

; #define WSP ws_(F)
;     __host__ __device__ __forceinline__ bool next(int i, Unit& u) const {
;         const long L = (long)i * G + c; if (L >= nwg) return false;
;         int wgid = (int)L; { const int q = nwg / NXCD, r = nwg % NXCD, xcd = wgid % NXCD, off = wgid / NXCD; wgid = (xcd < r ? xcd * (q + 1) : r * (q + 1) + (xcd - r) * q) + off; }
;         const int nig = WGM * nN, gid = wgid / nig, fm = gid * WGM, gsz = (nM - fm) < WGM ? (nM - fm) : WGM;
;         u.pm = fm + ((wgid % nig) % gsz); u.pn = (wgid % nig) / gsz; return true;
; __global__ void __launch_bounds__(NWAVES * 64, 2) mk_fwd(Args args) {
;     ...
;         _Pragma("unroll") for (int rep = 0; rep < DUPKV; ++rep) { pg8::Epi8<FKV> e{{(bf16*)(WSP + WS_KB), (bf16*)(WSP + WS_VB)}}; run_gemm(F, (const bf16*)(WSP + WS_CQKV) + 384, CQKV_LD, (const bf16*)(WSP + WS_WUKV), 256, TT, 1024, 256, e); }
.LBB0_819:
	s_mov_b32 s99, s97
	s_cmpk_lg_i32 s94, 0x100
	s_cbranch_scc1 .Lkv_rot_done
	s_add_i32 s99, s97, 58
	s_and_b32 s99, s99, 0xff
.Lkv_rot_done:
	s_cmpk_lt_i32 s99, 0x108
	s_cselect_b64 s[2:3], -1, 0
	s_add_i32 s0, 0, 0x204f8
	v_mov_b32_e32 v1, s0
	ds_read_b64 v[2:3], v1
	v_mov_b32_e32 v10, v0
	s_cmpk_gt_i32 s99, 0x107
	s_waitcnt lgkmcnt(0)
	v_readfirstlane_b32 s0, v2
	v_readfirstlane_b32 s1, v3
	v_readfirstlane_b32 s12, v10
	s_cbranch_scc1 .LBB0_821
	s_lshr_b32 s4, s40, 29
	s_add_i32 s4, s99, s4
	s_and_b32 s5, s4, -8
	s_sub_i32 s5, s99, s5
	s_cmp_lt_i32 s5, 0
	s_cselect_b32 s6, 34, 33
	s_mul_i32 s5, s6, s5
	s_ashr_i32 s4, s4, 3
	s_add_i32 s4, s5, s4
	s_ashr_i32 s5, s4, 31
	s_lshr_b32 s5, s5, 27
	s_add_i32 s5, s4, s5
	s_ashr_i32 s5, s5, 5
	s_lshl_b32 s6, s5, 3
	s_sub_i32 s7, 0x42, s6
	s_lshl_b32 s5, s5, 5
	s_min_u32 s7, s7, 8
	s_sub_i32 s8, s4, s5
	s_sext_i32_i8 s4, s8
	v_cvt_f32_ubyte0_e32 v2, s7
	v_cvt_f32_i32_e32 v1, s4
	v_rcp_iflag_f32_e32 v3, v2
	s_ashr_i32 s4, s4, 30
	s_or_b32 s9, s4, 1
	v_mul_f32_e32 v3, v1, v3
	v_trunc_f32_e32 v3, v3
	v_fma_f32 v1, -v3, v2, v1
	v_cvt_i32_f32_e32 v3, v3
	v_cmp_ge_f32_e64 s[4:5], |v1|, v2
	s_and_b64 s[4:5], s[4:5], exec
	s_cselect_b32 s4, s9, 0
	v_readfirstlane_b32 s5, v3
	s_add_i32 s5, s5, s4
	s_sext_i32_i8 s4, s5
	s_mul_i32 s5, s5, s7
	s_sub_i32 s5, s8, s5
	s_sext_i32_i8 s5, s5
	s_add_i32 s65, s6, s5

;     __host__ __device__ __forceinline__ bool next(int i, Unit& u) const {
;         const long L = (long)i * G + c; if (L >= nwg) return false;
;         int wgid = (int)L; { const int q = nwg / NXCD, r = nwg % NXCD, xcd = wgid % NXCD, off = wgid / NXCD; wgid = (xcd < r ? xcd * (q + 1) : r * (q + 1) + (xcd - r) * q) + off; }
;         const int nig = WGM * nN, gid = wgid / nig, fm = gid * WGM, gsz = (nM - fm) < WGM ? (nM - fm) : WGM;
;         u.pm = fm + ((wgid % nig) % gsz); u.pn = (wgid % nig) / gsz; return true;
; template <class Epi, class Sched, bool ALIGN_EPI = false, bool SP2 = false>
; __device__ __forceinline__ void gemm_phase(PG8_LAS unsigned char* lds, const Gemm g, const Sched& S, const Epi& E) {
;     ...
;         const bool has_next = S.next(ui + 1, nxt);
.LBB0_827:
	s_add_i32 s51, s51, 1
	s_mul_i32 s0, s51, s33
	s_mul_hi_u32 s1, s51, s94
	s_add_i32 s1, s1, s0
	s_mul_i32 s0, s51, s94
	s_add_u32 s2, s0, s99
	s_addc_u32 s3, s1, s40
	v_cmp_gt_i64_e32 vcc, s[2:3], v[146:147]
	v_cmp_lt_i64_e64 s[0:1], s[2:3], v[144:145]
	s_cbranch_vccnz .LBB0_829
	s_ashr_i32 s3, s2, 31
	s_lshr_b32 s3, s3, 29
	s_add_i32 s3, s2, s3
	s_ashr_i32 s5, s3, 3
	s_and_b32 s3, s3, -8
	s_sub_i32 s2, s2, s3
	s_cmp_lt_i32 s2, 0
	s_cselect_b32 s3, 34, 33
	s_mul_i32 s2, s3, s2
	s_add_i32 s2, s2, s5
	s_ashr_i32 s3, s2, 31
	s_lshr_b32 s3, s3, 27
	s_add_i32 s3, s2, s3
	s_ashr_i32 s5, s3, 5
	s_lshl_b32 s5, s5, 3
	s_sub_i32 s16, 0x42, s5
	s_min_i32 s17, s16, 8
	s_abs_i32 s16, s17
	v_cvt_f32_u32_e32 v2, s16
	s_sub_i32 s19, 0, s16
	s_andn2_b32 s3, s3, 31
	s_sub_i32 s2, s2, s3
	v_rcp_iflag_f32_e32 v2, v2
	s_abs_i32 s3, s2
	s_xor_b32 s18, s2, s17
	s_ashr_i32 s18, s18, 31
	v_mul_f32_e32 v2, 0x4f7ffffe, v2
	v_cvt_u32_f32_e32 v2, v2
	s_nop 0
	v_readfirstlane_b32 s20, v2
	s_mul_i32 s19, s19, s20
	s_mul_hi_u32 s19, s20, s19
	s_add_i32 s20, s20, s19
	s_mul_hi_u32 s19, s3, s20
	s_mul_i32 s20, s19, s16
	s_sub_i32 s3, s3, s20
	s_add_i32 s21, s19, 1
	s_sub_i32 s20, s3, s16
	s_cmp_ge_u32 s3, s16
	s_cselect_b32 s19, s21, s19
	s_cselect_b32 s3, s20, s3
	s_add_i32 s20, s19, 1
	s_cmp_ge_u32 s3, s16
	s_cselect_b32 s3, s20, s19
	s_xor_b32 s3, s3, s18
	s_sub_i32 s16, s3, s18
	s_mul_i32 s3, s16, s17
	s_sub_i32 s2, s2, s3
	s_add_i32 s64, s2, s5

; #define GAS __attribute__((address_space(1)))
; #define LAS __attribute__((address_space(3)))
; __device__ __forceinline__ v4u pack8(const float* x) { v4u w; w.x = pk2(x[0], x[1]); w.y = pk2(x[2], x[3]); w.z = pk2(x[4], x[5]); w.w = pk2(x[6], x[7]); return w; }
; __device__ __forceinline__ void ph_s5_out(Frame& F) {
;     ...
;     for (int u = F.vcu; u < 288; u += F.G) {
;         const int g = u / 9, nb = u % 9; int chunk = nb * 32 + r32; const bool valid = chunk < NCH; if (!valid) chunk = NCH - 1;
;         __syncthreads();
;         { const GAS v4u* tp = (const GAS v4u*)((const bf16*)(ws + WS_TOEP) + (size_t)g * 127 * 256); const float* t0 = (const float*)(ws + WS_T0) + (size_t)g * 512;
;           for (int c = tid; c < 127 * 32; c += 512) { const int di = c >> 5, p = (c >> 1) & 15, half = c & 1; v4u v;
;               if (di == 63) { float o[8];
; #pragma unroll
;                   for (int j = 0; j < 8; ++j) o[j] = t0[p * 16 + half * 8 + j] + t0[256 + p * 16 + half * 8 + j];
;                   v = pack8(o); }
;               else v = tp[c];
;               *(LAS v4u*)(L + (di * 16 + p) * TP_PITCH + half * 16) = v; } }
;         __syncthreads();
;         const bf16* ub = ug_frag_base(ws, g, nb, lane);
;         f32x16 acc[4];
; #pragma unroll
;         for (int i = 0; i < 4; ++i)
; #pragma unroll
;             for (int r = 0; r < 16; ++r) acc[i][r] = 0.f;
;         const LAS unsigned char* tl = L + ((63 + 2 * wave + (r32 >> 4)) * 16 + (r32 & 15)) * TP_PITCH + hh * 16;
; #pragma unroll 1
;         for (int s0 = 0; s0 < 64; s0 += 16) {
;             bf16x8_t bq[16];
; #pragma unroll
;             for (int e = 0; e < 16; ++e) bq[e] = *(const GAS bf16x8_t*)(ub + 512 * (s0 + e));
.LBB0_964:
	s_mul_hi_i32 s24, s48, 0x38e38e39
	s_lshr_b32 s25, s24, 31
	s_ashr_i32 s24, s24, 1
	s_add_i32 s26, s24, s25
	s_ashr_i32 s27, s26, 31
	s_barrier
	s_and_saveexec_b64 s[24:25], s[2:3]
	s_cbranch_execz .LBB0_971
	s_lshl_b64 s[28:29], s[26:27], 11
	s_add_u32 s28, s36, s28
	v_mad_i64_i32 v[6:7], s[30:31], s26, v93, v[74:75]
	s_addc_u32 s29, s37, s29
	v_lshrrev_b32_e32 v216, 5, v236
	v_bfe_u32 v10, v236, 1, 4
	v_lshl_or_b32 v216, v216, 4, v10
	v_mad_u32_u24 v216, v216, 48, v72
	v_add_u32_e32 v217, 0xc000, v216
	global_load_dwordx4 v[142:145], v[6:7], off
	v_lshl_add_u64 v[214:215], v[6:7], 0, s[20:21]
	global_load_dwordx4 v[146:149], v[214:215], off
	v_lshl_add_u64 v[214:215], v[214:215], 0, s[20:21]
	global_load_dwordx4 v[150:153], v[214:215], off
	v_lshl_add_u64 v[214:215], v[214:215], 0, s[20:21]
	global_load_dwordx4 v[154:157], v[214:215], off
	v_lshl_add_u64 v[214:215], v[214:215], 0, s[20:21]
	global_load_dwordx4 v[158:161], v[214:215], off
	v_lshl_add_u64 v[214:215], v[214:215], 0, s[20:21]
	global_load_dwordx4 v[162:165], v[214:215], off
	v_lshl_add_u64 v[214:215], v[214:215], 0, s[20:21]
	global_load_dwordx4 v[166:169], v[214:215], off
	v_lshl_add_u64 v[214:215], v[214:215], 0, s[20:21]
	v_cmp_gt_u32_e32 vcc, 0x1e0, v236
	s_and_saveexec_b64 s[30:31], vcc
	global_load_dwordx4 v[170:173], v[214:215], off
	s_andn2_b64 exec, s[30:31], exec
	s_cbranch_execz .Ls5_t0_done
	v_lshl_or_b32 v11, v10, 6, v92
	global_load_dwordx4 v[174:177], v11, s[28:29] offset:1024
	global_load_dwordx4 v[178:181], v11, s[28:29]
	global_load_dwordx4 v[182:185], v11, s[28:29] offset:16
	global_load_dwordx4 v[190:193], v11, s[28:29] offset:1040
	s_waitcnt vmcnt(0)
	v_pk_add_f32 v[174:175], v[178:179], v[174:175]
	v_pk_add_f32 v[176:177], v[180:181], v[176:177]
	v_pk_add_f32 v[178:179], v[182:183], v[190:191]
	v_pk_add_f32 v[180:181], v[184:185], v[192:193]
	v_cvt_pk_bf16_f32 v154, v174, v175
	v_cvt_pk_bf16_f32 v155, v176, v177
	v_cvt_pk_bf16_f32 v156, v178, v179
	v_cvt_pk_bf16_f32 v157, v180, v181
.Ls5_t0_done:
	s_mov_b64 exec, s[30:31]
	s_waitcnt vmcnt(0)
	s_and_b64 exec, s[30:31], vcc
	ds_write_b128 v217, v[170:173] offset:36864
	s_mov_b64 exec, s[30:31]
	ds_write_b128 v216, v[142:145]
	ds_write_b128 v216, v[146:149] offset:12288
	ds_write_b128 v216, v[150:153] offset:24576
	ds_write_b128 v216, v[154:157] offset:36864
	ds_write_b128 v216, v[158:161] offset:49152
	ds_write_b128 v216, v[162:165] offset:61440
	ds_write_b128 v217, v[166:169] offset:24576
.LBB0_971:
	s_or_b64 exec, exec, s[24:25]
	s_mul_i32 s24, s26, 9
	s_sub_i32 s24, s48, s24
	s_lshl_b32 s30, s26, 3
	s_add_i32 s25, s30, s24
	s_cmp_lt_i32 s24, 8
	s_cselect_b32 s28, s25, s26
	s_cselect_b32 s25, s41, 0xdc00000
	s_ashr_i32 s29, s28, 31
	s_lshl_b64 s[28:29], s[28:29], 16
	s_add_u32 s28, s25, s28
	s_addc_u32 s29, 0, s29
	v_mov_b32_e32 v50, 0
	v_lshl_add_u64 v[82:83], v[76:77], 0, s[28:29]
	s_mov_b32 s25, -16
	v_mov_b32_e32 v68, v91
	v_mov_b32_e32 v51, v50
	v_mov_b32_e32 v52, v50
	v_mov_b32_e32 v53, v50
	v_mov_b32_e32 v54, v50
	v_mov_b32_e32 v55, v50
	v_mov_b32_e32 v56, v50
	v_mov_b32_e32 v57, v50
	v_mov_b32_e32 v58, v50
	v_mov_b32_e32 v59, v50
	v_mov_b32_e32 v60, v50
	v_mov_b32_e32 v61, v50
	v_mov_b32_e32 v62, v50
	v_mov_b32_e32 v63, v50
	v_mov_b32_e32 v64, v50
	v_mov_b32_e32 v65, v50
	v_mov_b32_e32 v34, v50
	v_mov_b32_e32 v35, v50
	v_mov_b32_e32 v36, v50
	v_mov_b32_e32 v37, v50
	v_mov_b32_e32 v38, v50
	v_mov_b32_e32 v39, v50
	v_mov_b32_e32 v40, v50
	v_mov_b32_e32 v41, v50
	v_mov_b32_e32 v42, v50
	v_mov_b32_e32 v43, v50
	v_mov_b32_e32 v44, v50
	v_mov_b32_e32 v45, v50
	v_mov_b32_e32 v46, v50
	v_mov_b32_e32 v47, v50
	v_mov_b32_e32 v48, v50
	v_mov_b32_e32 v49, v50
	v_mov_b32_e32 v18, v50
	v_mov_b32_e32 v19, v50
	v_mov_b32_e32 v20, v50
	v_mov_b32_e32 v21, v50
	v_mov_b32_e32 v22, v50
	v_mov_b32_e32 v23, v50
	v_mov_b32_e32 v24, v50
	v_mov_b32_e32 v25, v50
	v_mov_b32_e32 v26, v50
	v_mov_b32_e32 v27, v50
	v_mov_b32_e32 v28, v50
	v_mov_b32_e32 v29, v50
	v_mov_b32_e32 v30, v50
	v_mov_b32_e32 v31, v50
	v_mov_b32_e32 v32, v50
	v_mov_b32_e32 v33, v50
	v_mov_b32_e32 v2, v50
	v_mov_b32_e32 v3, v50
	v_mov_b32_e32 v4, v50
	v_mov_b32_e32 v5, v50
	v_mov_b32_e32 v6, v50
	v_mov_b32_e32 v7, v50
	v_mov_b32_e32 v8, v50
	v_mov_b32_e32 v9, v50
	v_mov_b32_e32 v10, v50
	v_mov_b32_e32 v11, v50
	v_mov_b32_e32 v12, v50
	v_mov_b32_e32 v13, v50
	v_mov_b32_e32 v14, v50
	v_mov_b32_e32 v15, v50
	v_mov_b32_e32 v16, v50
	v_mov_b32_e32 v17, v50
	s_waitcnt lgkmcnt(0)
	s_barrier
	v_add_co_u32_e32 v82, vcc, 0xffffc000, v82
	s_nop 1
	v_addc_co_u32_e32 v83, vcc, -1, v83, vcc
	v_add_co_u32_e32 v210, vcc, 0x2000, v82
	s_nop 1
	v_addc_co_u32_e32 v211, vcc, 0, v83, vcc
	v_add_co_u32_e32 v212, vcc, 0x4000, v82
	s_nop 1
	v_addc_co_u32_e32 v213, vcc, 0, v83, vcc
	global_load_dwordx4 v[142:145], v[82:83], off offset:1024
	global_load_dwordx4 v[146:149], v[82:83], off offset:2048
	global_load_dwordx4 v[150:153], v[82:83], off offset:3072
	global_load_dwordx4 v[154:157], v[210:211], off offset:-4096
	global_load_dwordx4 v[158:161], v[210:211], off offset:-3072
	global_load_dwordx4 v[162:165], v[210:211], off offset:-2048
	global_load_dwordx4 v[166:169], v[210:211], off offset:-1024
	global_load_dwordx4 v[170:173], v[210:211], off offset:0
	global_load_dwordx4 v[174:177], v[210:211], off offset:1024
	global_load_dwordx4 v[178:181], v[210:211], off offset:2048
	global_load_dwordx4 v[182:185], v[210:211], off offset:3072
	global_load_dwordx4 v[190:193], v[212:213], off offset:-4096
	global_load_dwordx4 v[194:197], v[212:213], off offset:-3072
	global_load_dwordx4 v[198:201], v[212:213], off offset:-2048
	global_load_dwordx4 v[202:205], v[212:213], off offset:-1024
	global_load_dwordx4 v[206:209], v[212:213], off offset:0
	v_lshl_add_u64 v[82:83], v[82:83], 0, s[22:23]
; #define GAS __attribute__((address_space(1)))
; #define LAS __attribute__((address_space(3)))
; __device__ __forceinline__ void ph_s5_out(Frame& F) {
;     ...
;         for (int s0 = 0; s0 < 64; s0 += 16) {
;             bf16x8_t bq[16];
; #pragma unroll
;             for (int e = 0; e < 16; ++e) bq[e] = *(const GAS bf16x8_t*)(ub + 512 * (s0 + e));
; #pragma unroll
;             for (int e = 0; e < 16; ++e) { const int sI = s0 + e; const bf16x8_t b = bq[e];
; #pragma unroll
;             for (int i = 0; i < 4; ++i) { const bf16x8_t a = *(const LAS bf16x8_t*)(tl + (16 * i - sI) * 16 * TP_PITCH); acc[i] = __builtin_amdgcn_mfma_f32_32x32x16_bf16(a, b, acc[i], 0, 0, 0); }
;             }
;         }
.LBB0_972:
	v_add_co_u32_e32 v210, vcc, 0x2000, v82
	s_nop 1
	v_addc_co_u32_e32 v211, vcc, 0, v83, vcc
	v_add_co_u32_e32 v212, vcc, 0x4000, v82
	s_nop 1
	v_addc_co_u32_e32 v213, vcc, 0, v83, vcc
	ds_read_b128 v[84:87], v68 offset:11520
	ds_read_b128 v[96:99], v68 offset:12288
	s_waitcnt vmcnt(15) lgkmcnt(1)
	v_mfma_f32_32x32x16_bf16 v[50:65], v[84:87], v[142:145], v[50:65]
	ds_read_b128 v[84:87], v68 offset:23808
	ds_read_b128 v[108:111], v68 offset:24576
	s_waitcnt lgkmcnt(1)
	v_mfma_f32_32x32x16_bf16 v[34:49], v[84:87], v[142:145], v[34:49]
	ds_read_b128 v[84:87], v68 offset:36096
	ds_read_b128 v[112:115], v68 offset:36864
	s_waitcnt lgkmcnt(1)
	v_mfma_f32_32x32x16_bf16 v[18:33], v[84:87], v[142:145], v[18:33]
	ds_read_b128 v[84:87], v68 offset:48384
	ds_read_b128 v[116:119], v68
	s_waitcnt lgkmcnt(1)
	v_mfma_f32_32x32x16_bf16 v[2:17], v[84:87], v[142:145], v[2:17]
	global_load_dwordx4 v[142:145], v[82:83], off offset:1024
	ds_read_b128 v[84:87], v68 offset:10752
	ds_read_b128 v[100:103], v68 offset:9984
	s_waitcnt vmcnt(15) lgkmcnt(1)
	v_mfma_f32_32x32x16_bf16 v[50:65], v[84:87], v[146:149], v[50:65]
	ds_read_b128 v[84:87], v68 offset:23040
	ds_read_b128 v[120:123], v68 offset:22272
	s_waitcnt lgkmcnt(1)
	v_mfma_f32_32x32x16_bf16 v[34:49], v[84:87], v[146:149], v[34:49]
	ds_read_b128 v[84:87], v68 offset:35328
	ds_read_b128 v[124:127], v68 offset:34560
	ds_read_b128 v[128:131], v68 offset:46848
	s_waitcnt lgkmcnt(2)
	v_mfma_f32_32x32x16_bf16 v[18:33], v[84:87], v[146:149], v[18:33]
	ds_read_b128 v[84:87], v68 offset:47616
	s_waitcnt lgkmcnt(0)
	v_mfma_f32_32x32x16_bf16 v[2:17], v[84:87], v[146:149], v[2:17]
	global_load_dwordx4 v[146:149], v[82:83], off offset:2048
	s_waitcnt vmcnt(15)
	v_mfma_f32_32x32x16_bf16 v[50:65], v[100:103], v[150:153], v[50:65]
	v_mfma_f32_32x32x16_bf16 v[34:49], v[120:123], v[150:153], v[34:49]
	ds_read_b128 v[100:103], v68 offset:9216
	ds_read_b128 v[120:123], v68 offset:8448
	v_mfma_f32_32x32x16_bf16 v[18:33], v[124:127], v[150:153], v[18:33]
	v_mfma_f32_32x32x16_bf16 v[2:17], v[128:131], v[150:153], v[2:17]
	global_load_dwordx4 v[150:153], v[82:83], off offset:3072
	s_waitcnt vmcnt(15) lgkmcnt(1)
	v_mfma_f32_32x32x16_bf16 v[50:65], v[100:103], v[154:157], v[50:65]
	ds_read_b128 v[100:103], v68 offset:21504
	ds_read_b128 v[128:131], v68 offset:20736
	s_waitcnt lgkmcnt(1)
	v_mfma_f32_32x32x16_bf16 v[34:49], v[100:103], v[154:157], v[34:49]
	ds_read_b128 v[100:103], v68 offset:33792
	ds_read_b128 v[132:135], v68 offset:33024
	s_waitcnt lgkmcnt(1)
	v_mfma_f32_32x32x16_bf16 v[18:33], v[100:103], v[154:157], v[18:33]
	ds_read_b128 v[100:103], v68 offset:46080
	ds_read_b128 v[136:139], v68 offset:45312
	s_waitcnt lgkmcnt(1)
	v_mfma_f32_32x32x16_bf16 v[2:17], v[100:103], v[154:157], v[2:17]
	global_load_dwordx4 v[154:157], v[210:211], off offset:-4096
	s_waitcnt vmcnt(15)
	v_mfma_f32_32x32x16_bf16 v[50:65], v[120:123], v[158:161], v[50:65]
	ds_read_b128 v[100:103], v68 offset:7680
	ds_read_b128 v[120:123], v68 offset:6912
	v_mfma_f32_32x32x16_bf16 v[34:49], v[128:131], v[158:161], v[34:49]
	v_mfma_f32_32x32x16_bf16 v[18:33], v[132:135], v[158:161], v[18:33]
	s_waitcnt lgkmcnt(2)
	v_mfma_f32_32x32x16_bf16 v[2:17], v[136:139], v[158:161], v[2:17]
	global_load_dwordx4 v[158:161], v[210:211], off offset:-3072
	s_waitcnt vmcnt(15) lgkmcnt(1)
	v_mfma_f32_32x32x16_bf16 v[50:65], v[100:103], v[162:165], v[50:65]
	ds_read_b128 v[100:103], v68 offset:19968
	ds_read_b128 v[128:131], v68 offset:19200
	s_waitcnt lgkmcnt(1)
	v_mfma_f32_32x32x16_bf16 v[34:49], v[100:103], v[162:165], v[34:49]
	ds_read_b128 v[100:103], v68 offset:32256
	ds_read_b128 v[132:135], v68 offset:31488
	s_waitcnt lgkmcnt(1)
	v_mfma_f32_32x32x16_bf16 v[18:33], v[100:103], v[162:165], v[18:33]
	ds_read_b128 v[100:103], v68 offset:44544
	ds_read_b128 v[136:139], v68 offset:43776
	s_waitcnt lgkmcnt(1)
	v_mfma_f32_32x32x16_bf16 v[2:17], v[100:103], v[162:165], v[2:17]
	global_load_dwordx4 v[162:165], v[210:211], off offset:-2048
	s_waitcnt vmcnt(15)
	v_mfma_f32_32x32x16_bf16 v[50:65], v[120:123], v[166:169], v[50:65]
	ds_read_b128 v[100:103], v68 offset:6144
	ds_read_b128 v[120:123], v68 offset:5376
	v_mfma_f32_32x32x16_bf16 v[34:49], v[128:131], v[166:169], v[34:49]
	v_mfma_f32_32x32x16_bf16 v[18:33], v[132:135], v[166:169], v[18:33]
	s_waitcnt lgkmcnt(2)
	v_mfma_f32_32x32x16_bf16 v[2:17], v[136:139], v[166:169], v[2:17]
	global_load_dwordx4 v[166:169], v[210:211], off offset:-1024
	s_waitcnt vmcnt(15) lgkmcnt(1)
	v_mfma_f32_32x32x16_bf16 v[50:65], v[100:103], v[170:173], v[50:65]
	ds_read_b128 v[100:103], v68 offset:18432
	ds_read_b128 v[124:127], v68 offset:17664
	s_waitcnt lgkmcnt(1)
	v_mfma_f32_32x32x16_bf16 v[34:49], v[100:103], v[170:173], v[34:49]
	ds_read_b128 v[100:103], v68 offset:30720
	ds_read_b128 v[128:131], v68 offset:29952
	s_waitcnt lgkmcnt(1)
; #define GAS __attribute__((address_space(1)))
; #define LAS __attribute__((address_space(3)))
; __device__ __forceinline__ void ph_s5_out(Frame& F) {
;     ...
;         for (int s0 = 0; s0 < 64; s0 += 16) {
;             bf16x8_t bq[16];
; #pragma unroll
;             for (int e = 0; e < 16; ++e) bq[e] = *(const GAS bf16x8_t*)(ub + 512 * (s0 + e));
; #pragma unroll
;             for (int e = 0; e < 16; ++e) { const int sI = s0 + e; const bf16x8_t b = bq[e];
; #pragma unroll
;             for (int i = 0; i < 4; ++i) { const bf16x8_t a = *(const LAS bf16x8_t*)(tl + (16 * i - sI) * 16 * TP_PITCH); acc[i] = __builtin_amdgcn_mfma_f32_32x32x16_bf16(a, b, acc[i], 0, 0, 0); }
;             }
;         }
;         { const bf16* sb = (const bf16*)(ws + WS_SIN) + (size_t)g * 9 * 16 * 512 + ((size_t)nb * 16 * 64 + lane) * 8;
;           const bf16* wc = (const bf16*)(ws + WS_WC) + (size_t)g * 1024 * 256 + (((size_t)wave * 16) * 64 + lane) * 8;
	v_mfma_f32_32x32x16_bf16 v[18:33], v[100:103], v[170:173], v[18:33]
	ds_read_b128 v[100:103], v68 offset:43008
	ds_read_b128 v[132:135], v68 offset:42240
	s_waitcnt lgkmcnt(1)
	v_mfma_f32_32x32x16_bf16 v[2:17], v[100:103], v[170:173], v[2:17]
	global_load_dwordx4 v[170:173], v[210:211], off offset:0
	ds_read_b128 v[84:87], v68 offset:4608
	ds_read_b128 v[100:103], v68 offset:3840
	s_waitcnt vmcnt(15)
	v_mfma_f32_32x32x16_bf16 v[50:65], v[120:123], v[174:177], v[50:65]
	v_mfma_f32_32x32x16_bf16 v[34:49], v[124:127], v[174:177], v[34:49]
	v_mfma_f32_32x32x16_bf16 v[18:33], v[128:131], v[174:177], v[18:33]
	s_waitcnt lgkmcnt(2)
	v_mfma_f32_32x32x16_bf16 v[2:17], v[132:135], v[174:177], v[2:17]
	global_load_dwordx4 v[174:177], v[210:211], off offset:1024
	s_waitcnt vmcnt(15) lgkmcnt(1)
	v_mfma_f32_32x32x16_bf16 v[50:65], v[84:87], v[178:181], v[50:65]
	ds_read_b128 v[84:87], v68 offset:16896
	ds_read_b128 v[124:127], v68 offset:16128
	s_waitcnt lgkmcnt(1)
	v_mfma_f32_32x32x16_bf16 v[34:49], v[84:87], v[178:181], v[34:49]
	ds_read_b128 v[84:87], v68 offset:29184
	ds_read_b128 v[128:131], v68 offset:28416
	s_waitcnt lgkmcnt(1)
	v_mfma_f32_32x32x16_bf16 v[18:33], v[84:87], v[178:181], v[18:33]
	ds_read_b128 v[84:87], v68 offset:41472
	ds_read_b128 v[132:135], v68 offset:40704
	s_waitcnt lgkmcnt(1)
	v_mfma_f32_32x32x16_bf16 v[2:17], v[84:87], v[178:181], v[2:17]
	global_load_dwordx4 v[178:181], v[210:211], off offset:2048
	s_waitcnt vmcnt(15)
	v_mfma_f32_32x32x16_bf16 v[50:65], v[100:103], v[182:185], v[50:65]
	v_mfma_f32_32x32x16_bf16 v[34:49], v[124:127], v[182:185], v[34:49]
	v_mfma_f32_32x32x16_bf16 v[18:33], v[128:131], v[182:185], v[18:33]
	s_waitcnt lgkmcnt(0)
	v_mfma_f32_32x32x16_bf16 v[2:17], v[132:135], v[182:185], v[2:17]
	global_load_dwordx4 v[182:185], v[210:211], off offset:3072
	ds_read_b128 v[104:107], v68 offset:3072
	ds_read_b128 v[120:123], v68 offset:2304
	s_waitcnt vmcnt(15) lgkmcnt(1)
	v_mfma_f32_32x32x16_bf16 v[50:65], v[104:107], v[190:193], v[50:65]
	ds_read_b128 v[104:107], v68 offset:15360
	ds_read_b128 v[124:127], v68 offset:14592
	s_waitcnt lgkmcnt(1)
	v_mfma_f32_32x32x16_bf16 v[34:49], v[104:107], v[190:193], v[34:49]
	ds_read_b128 v[104:107], v68 offset:27648
	ds_read_b128 v[128:131], v68 offset:26880
	s_waitcnt lgkmcnt(1)
	v_mfma_f32_32x32x16_bf16 v[18:33], v[104:107], v[190:193], v[18:33]
	ds_read_b128 v[104:107], v68 offset:39936
	ds_read_b128 v[132:135], v68 offset:39168
	s_waitcnt lgkmcnt(1)
	v_mfma_f32_32x32x16_bf16 v[2:17], v[104:107], v[190:193], v[2:17]
	global_load_dwordx4 v[190:193], v[212:213], off offset:-4096
	s_waitcnt vmcnt(15)
	v_mfma_f32_32x32x16_bf16 v[50:65], v[120:123], v[194:197], v[50:65]
	v_mfma_f32_32x32x16_bf16 v[34:49], v[124:127], v[194:197], v[34:49]
	v_mfma_f32_32x32x16_bf16 v[18:33], v[128:131], v[194:197], v[18:33]
	s_waitcnt lgkmcnt(0)
	v_mfma_f32_32x32x16_bf16 v[2:17], v[132:135], v[194:197], v[2:17]
	global_load_dwordx4 v[194:197], v[212:213], off offset:-3072
	ds_read_b128 v[100:103], v68 offset:1536
	ds_read_b128 v[120:123], v68 offset:768
	s_waitcnt vmcnt(15) lgkmcnt(1)
	v_mfma_f32_32x32x16_bf16 v[50:65], v[100:103], v[198:201], v[50:65]
	ds_read_b128 v[100:103], v68 offset:13824
	ds_read_b128 v[124:127], v68 offset:13056
	s_waitcnt lgkmcnt(1)
	v_mfma_f32_32x32x16_bf16 v[34:49], v[100:103], v[198:201], v[34:49]
	ds_read_b128 v[100:103], v68 offset:26112
	ds_read_b128 v[128:131], v68 offset:25344
	s_waitcnt lgkmcnt(1)
	v_mfma_f32_32x32x16_bf16 v[18:33], v[100:103], v[198:201], v[18:33]
	ds_read_b128 v[100:103], v68 offset:38400
	ds_read_b128 v[132:135], v68 offset:37632
	v_add_u32_e32 v68, 0xffffd000, v68
	s_waitcnt lgkmcnt(1)
	v_mfma_f32_32x32x16_bf16 v[2:17], v[100:103], v[198:201], v[2:17]
	global_load_dwordx4 v[198:201], v[212:213], off offset:-2048
	s_waitcnt vmcnt(15)
	v_mfma_f32_32x32x16_bf16 v[50:65], v[120:123], v[202:205], v[50:65]
	v_mfma_f32_32x32x16_bf16 v[34:49], v[124:127], v[202:205], v[34:49]
	v_mfma_f32_32x32x16_bf16 v[18:33], v[128:131], v[202:205], v[18:33]
	s_waitcnt lgkmcnt(0)
	v_mfma_f32_32x32x16_bf16 v[2:17], v[132:135], v[202:205], v[2:17]
	global_load_dwordx4 v[202:205], v[212:213], off offset:-1024
	s_waitcnt vmcnt(15)
	v_mfma_f32_32x32x16_bf16 v[50:65], v[116:119], v[206:209], v[50:65]
	v_mfma_f32_32x32x16_bf16 v[34:49], v[96:99], v[206:209], v[34:49]
	v_mfma_f32_32x32x16_bf16 v[18:33], v[108:111], v[206:209], v[18:33]
	v_mfma_f32_32x32x16_bf16 v[2:17], v[112:115], v[206:209], v[2:17]
	global_load_dwordx4 v[206:209], v[212:213], off offset:0
	v_lshl_add_u64 v[82:83], v[82:83], 0, s[22:23]
	s_add_i32 s25, s25, 16
	s_cmp_gt_u32 s25, 47
	s_cbranch_scc0 .LBB0_972
	s_ashr_i32 s25, s24, 31
	s_mul_i32 s49, s26, 0x24000
	s_lshl_b64 s[28:29], s[24:25], 14
	s_lshl_b64 s[34:35], s[26:27], 19
	s_mul_hi_i32 s31, s26, 0x24000
	s_add_u32 s28, s49, s28
	s_addc_u32 s29, s31, s29
	v_lshl_add_u64 v[82:83], v[78:79], 0, s[34:35]
	v_lshl_add_u64 v[84:85], v[80:81], 0, s[28:29]
	s_mov_b64 s[28:29], 0

.LBB0_1004:
	v_mfma_f32_32x32x16_bf16 v[68:83], v[136:139], v[100:103], 0
	v_add_u32_e32 v2, s45, v189
	ds_read_b128 v[184:187], v2 offset:96
	ds_read_b128 v[210:213], v2 offset:128
	ds_read_b128 v[214:217], v2 offset:6752
	ds_read_b128 v[218:221], v2 offset:160
	ds_read_b128 v[222:225], v2 offset:6784
	ds_read_b128 v[226:229], v2 offset:6816
	v_add_u32_e32 v2, s39, v200
	ds_read_b128 v[176:179], v2 offset:53248
	ds_read_b128 v[164:167], v2 offset:53280
	ds_read_b128 v[230:233], v2 offset:57856
	ds_read_b128 v[238:241], v2 offset:57888
	ds_read_b128 v[160:163], v2 offset:53312
	ds_read_b128 v[156:159], v2 offset:53344
	ds_read_b128 v[242:245], v2 offset:57920
	ds_read_b128 v[152:155], v2 offset:57952
	v_sub_f32_e32 v2, v52, v180
	v_mfma_f32_32x32x16_bf16 v[84:99], v[132:135], v[100:103], 0
	v_exp_f32_e32 v52, v2
	v_sub_f32_e32 v2, v36, v180
	v_exp_f32_e32 v183, v2
	v_sub_f32_e32 v2, v53, v180
	v_exp_f32_e32 v132, v2
	v_sub_f32_e32 v2, v54, v180
	v_exp_f32_e32 v53, v2
	v_mfma_f32_32x32x16_bf16 v[68:83], v[144:147], v[104:107], v[68:83]
	v_sub_f32_e32 v2, v38, v180
	v_sub_f32_e32 v38, v56, v180
	v_sub_f32_e32 v36, v55, v180
	v_exp_f32_e32 v55, v38
	v_sub_f32_e32 v38, v40, v180
	v_sub_f32_e32 v42, v42, v180
	v_exp_f32_e32 v56, v38
	v_mfma_f32_32x32x16_bf16 v[84:99], v[128:131], v[104:107], v[84:99]
	v_sub_f32_e32 v38, v39, v180
	v_sub_f32_e32 v41, v41, v180
	v_exp_f32_e32 v40, v38
	v_sub_f32_e32 v38, v57, v180
	v_sub_f32_e32 v57, v58, v180
	v_exp_f32_e32 v58, v41
	v_sub_f32_e32 v41, v59, v180
	v_mfma_f32_32x32x16_bf16 v[68:83], v[140:143], v[108:111], v[68:83]
	v_add_u32_e32 v181, s44, v189
	ds_read_b128 v[144:147], v181
	ds_read_b128 v[172:175], v181 offset:32
	ds_read_b128 v[136:139], v181 offset:6656
	ds_read_b128 v[168:171], v181 offset:64
	ds_read_b128 v[148:151], v181 offset:6688
	ds_read_b128 v[140:143], v181 offset:6720
	v_exp_f32_e32 v54, v2
	v_sub_f32_e32 v2, v37, v180
	v_exp_f32_e32 v2, v2
	v_mfma_f32_32x32x16_bf16 v[84:99], v[124:127], v[108:111], v[84:99]
	v_exp_f32_e32 v124, v41
	v_sub_f32_e32 v41, v60, v180
	v_exp_f32_e32 v36, v36
	v_exp_f32_e32 v57, v57
	v_exp_f32_e32 v41, v41
	v_add_f32_e32 v133, v52, v183
	v_add_f32_e32 v37, v53, v54
	s_waitcnt lgkmcnt(14)
	v_mfma_f32_32x32x16_bf16 v[68:83], v[214:217], v[112:115], v[68:83]
	v_exp_f32_e32 v214, v42
	v_sub_f32_e32 v42, v44, v180
	v_exp_f32_e32 v59, v42
	v_sub_f32_e32 v42, v43, v180
	v_exp_f32_e32 v60, v42
	v_sub_f32_e32 v42, v61, v180
	v_exp_f32_e32 v126, v42
	v_mfma_f32_32x32x16_bf16 v[84:99], v[184:187], v[112:115], v[84:99]
	v_sub_f32_e32 v42, v45, v180
	v_sub_f32_e32 v43, v62, v180
	v_exp_f32_e32 v62, v42
	v_sub_f32_e32 v42, v63, v180
	v_exp_f32_e32 v128, v42
	v_sub_f32_e32 v42, v64, v180
	v_exp_f32_e32 v63, v42
	v_mfma_f32_32x32x16_bf16 v[68:83], v[222:225], v[116:119], v[68:83]
	v_sub_f32_e32 v42, v48, v180
	v_exp_f32_e32 v216, v42
	v_sub_f32_e32 v42, v47, v180
	v_exp_f32_e32 v64, v42
	v_sub_f32_e32 v42, v65, v180
	v_exp_f32_e32 v130, v42
	v_sub_f32_e32 v42, v66, v180
	v_mfma_f32_32x32x16_bf16 v[84:99], v[210:213], v[116:119], v[84:99]
	v_exp_f32_e32 v61, v43
	v_sub_f32_e32 v43, v46, v180
	v_exp_f32_e32 v65, v42
	v_sub_f32_e32 v42, v50, v180
	v_exp_f32_e32 v215, v43
	v_exp_f32_e32 v185, v42
	v_sub_f32_e32 v42, v49, v180
	v_mfma_f32_32x32x16_bf16 v[68:83], v[226:229], v[120:123], v[68:83]
	v_exp_f32_e32 v66, v42
	v_sub_f32_e32 v42, v67, v180
	v_exp_f32_e32 v134, v42
	v_sub_f32_e32 v42, v51, v180
	v_add_f32_e32 v39, v55, v56
	v_exp_f32_e32 v38, v38
	v_add_f32_e32 v125, v57, v214
	v_mfma_f32_32x32x16_bf16 v[84:99], v[218:221], v[120:123], v[84:99]
	v_add_f32_e32 v127, v41, v59
	v_add_f32_e32 v129, v61, v215
	v_add_f32_e32 v131, v63, v216
	v_add_f32_e32 v135, v65, v185
	v_exp_f32_e32 v184, v42
	v_cvt_pk_bf16_f32 v42, v52, v132
	v_cvt_pk_bf16_f32 v43, v53, v36
	v_cvt_pk_bf16_f32 v44, v55, v38
	v_cvt_pk_bf16_f32 v45, v57, v124
	v_cvt_pk_bf16_f32 v46, v41, v126
	v_cvt_pk_bf16_f32 v47, v61, v128
	v_cvt_pk_bf16_f32 v48, v63, v130
	v_cvt_pk_bf16_f32 v49, v65, v134
	v_cvt_pk_bf16_f32 v50, v183, v2
	v_cvt_pk_bf16_f32 v51, v54, v40
	v_cvt_pk_bf16_f32 v52, v56, v58
	v_cvt_pk_bf16_f32 v53, v214, v60
	v_cvt_pk_bf16_f32 v54, v59, v62
	v_cvt_pk_bf16_f32 v55, v215, v64
	v_cvt_pk_bf16_f32 v56, v216, v66
	v_cvt_pk_bf16_f32 v57, v185, v184
	s_add_i32 s14, s46, 5
	s_min_u32 s14, s14, s37
	s_add_i32 s15, s46, 3
	s_min_u32 s46, s15, s37
	s_mulk_i32 s14, 0x3000
	s_add_u32 s14, s10, s14
	s_addc_u32 s15, s11, 0
	s_lshl_b32 s46, s46, 13
	s_add_u32 s46, s12, s46
	s_addc_u32 s47, s13, 0
	s_add_i32 m0, s22, s45
	s_and_b64 s[48:49], s[4:5], exec
	s_waitcnt vmcnt(3) lgkmcnt(0)
	s_barrier
	v_lshl_add_u64 v[186:187], s[14:15], 0, v[190:191]
	s_cselect_b32 s15, s15, s47
	s_cselect_b32 s14, s14, s46
	global_load_lds_dwordx4 v[186:187], off
	v_lshl_add_u64 v[186:187], s[14:15], 0, v[192:193]
	s_cselect_b32 s14, s45, s39
	s_add_i32 m0, s21, s14
	s_add_i32 s14, s23, s39
	global_load_lds_dwordx4 v[186:187], off
	v_lshl_add_u64 v[186:187], s[46:47], 0, v[194:195]
	s_add_i32 m0, s14, 0xd000
	s_nop 0
	global_load_lds_dwordx4 v[186:187], off
	v_mfma_f32_32x32x16_bf16 v[4:19], v[42:45], v[230:233], v[4:19]
	v_max3_f32 v41, v84, v68, v85
	v_max3_f32 v59, v92, v76, v93
	v_add_f32_e32 v132, v132, v2
	v_max3_f32 v41, v41, v69, v86
	v_max3_f32 v59, v59, v77, v94
	s_nop 0
	v_max3_f32 v41, v41, v70, v87
	v_mfma_f32_32x32x16_bf16 v[20:35], v[42:45], v[176:179], v[20:35]
	v_max3_f32 v41, v41, v71, v88
	v_max3_f32 v59, v59, v78, v95
	v_max3_f32 v41, v41, v72, v89
	v_max3_f32 v59, v59, v79, v96
	s_nop 0
	v_max3_f32 v41, v41, v73, v90
	v_mfma_f32_32x32x16_bf16 v[4:19], v[46:49], v[238:241], v[4:19]
	v_max3_f32 v183, v41, v74, v91
	v_add_f32_e32 v41, v132, v133
	v_max3_f32 v59, v59, v80, v97
	v_add_f32_e64 v36, v36, v40
	v_add_f32_e64 v37, v37, v41
	v_max3_f32 v59, v59, v81, v98
	v_mfma_f32_32x32x16_bf16 v[20:35], v[46:49], v[164:167], v[20:35]
	v_max3_f32 v186, v59, v82, v99
	v_add_f32_e32 v59, v36, v37
	v_add_f32_e32 v36, v38, v58
	v_add_f32_e32 v37, v39, v59
	v_add_f32_e32 v61, v36, v37
	v_add_f32_e32 v36, v124, v60
	v_add_f32_e32 v37, v125, v61
	v_mfma_f32_32x32x16_bf16 v[4:19], v[50:53], v[242:245], v[4:19]
	v_add_f32_e32 v63, v36, v37
	v_add_f32_e32 v36, v126, v62
	v_add_f32_e32 v37, v127, v63
	v_add_f32_e32 v65, v36, v37
	v_add_f32_e32 v36, v128, v64
	v_add_f32_e32 v37, v129, v65
	v_mfma_f32_32x32x16_bf16 v[20:35], v[50:53], v[160:163], v[20:35]
	v_add_f32_e32 v67, v36, v37
	v_add_f32_e32 v36, v130, v66
	v_add_f32_e32 v37, v131, v67
	v_add_f32_e32 v185, v36, v37
	v_add_f32_e32 v36, v134, v184
	v_add_f32_e32 v37, v135, v185
	v_mfma_f32_32x32x16_bf16 v[20:35], v[54:57], v[156:159], v[20:35]
	v_add_f32_e32 v2, v36, v37
	v_max3_f32 v36, v183, v75, v186
	v_add_f32_e32 v2, v209, v2
	v_max3_f32 v36, v36, v83, v36
	s_nop 0
	v_mov_b32_e32 v37, v36
	v_mov_b32_e32 v38, v36
	v_mfma_f32_32x32x16_bf16 v[4:19], v[54:57], v[152:155], v[4:19]
	s_nop 0
	v_permlane32_swap_b32_e32 v37, v38
	v_max3_f32 v36, v37, v38, v36
	s_nop 0
	v_cmp_gt_f32_e32 vcc, v36, v182
	s_cbranch_vccz .LBB0_1008
	s_nop 0
	v_cndmask_b32_e32 v210, v180, v36, vcc
	v_sub_f32_e32 v36, v180, v210
	v_exp_f32_e32 v36, v36
	s_and_saveexec_b64 s[14:15], s[2:3]
	ds_write_b32 v202, v36
	s_or_b64 exec, exec, s[14:15]
	v_mul_f32_e32 v2, v2, v36
	ds_read_b32 v36, v1
	ds_read_b32 v37, v1 offset:4
	ds_read_b32 v38, v1 offset:8
	ds_read_b32 v39, v1 offset:12
	ds_read_b32 v40, v1 offset:32
	ds_read_b32 v41, v1 offset:36
	ds_read_b32 v42, v1 offset:40
	ds_read_b32 v43, v1 offset:44
	ds_read_b32 v44, v1 offset:64
	ds_read_b32 v45, v1 offset:68
	ds_read_b32 v46, v1 offset:72
	ds_read_b32 v47, v1 offset:76
	ds_read_b32 v48, v1 offset:96
	ds_read_b32 v49, v1 offset:100
	ds_read_b32 v50, v1 offset:104
	ds_read_b32 v51, v1 offset:108
	s_waitcnt lgkmcnt(0)
	v_pk_mul_f32 v[20:21], v[20:21], v[36:37]
	v_pk_mul_f32 v[22:23], v[22:23], v[38:39]
	v_pk_mul_f32 v[24:25], v[24:25], v[40:41]
	v_pk_mul_f32 v[26:27], v[26:27], v[42:43]
	v_pk_mul_f32 v[28:29], v[28:29], v[44:45]
	v_pk_mul_f32 v[30:31], v[30:31], v[46:47]
	v_pk_mul_f32 v[32:33], v[32:33], v[48:49]
	v_pk_mul_f32 v[34:35], v[34:35], v[50:51]
	v_pk_mul_f32 v[4:5], v[4:5], v[36:37]
	v_pk_mul_f32 v[6:7], v[6:7], v[38:39]
	v_pk_mul_f32 v[8:9], v[8:9], v[40:41]
	v_pk_mul_f32 v[10:11], v[10:11], v[42:43]
	v_pk_mul_f32 v[12:13], v[12:13], v[44:45]
	v_pk_mul_f32 v[14:15], v[14:15], v[46:47]
	v_pk_mul_f32 v[16:17], v[16:17], v[48:49]
	v_pk_mul_f32 v[18:19], v[18:19], v[50:51]
	s_branch .LBB0_1009

.LBB0_1009:
	v_mfma_f32_32x32x16_bf16 v[36:51], v[136:139], v[100:103], 0
	v_add_u32_e32 v52, s43, v200
	ds_read_b128 v[212:215], v181 offset:96
	ds_read_b128 v[216:219], v181 offset:128
	ds_read_b128 v[220:223], v181 offset:6752
	ds_read_b128 v[224:227], v181 offset:160
	ds_read_b128 v[228:231], v181 offset:6784
	ds_read_b128 v[238:241], v181 offset:6816
	ds_read_b128 v[160:163], v52 offset:53248
	ds_read_b128 v[164:167], v52 offset:53280
	ds_read_b128 v[184:187], v52 offset:57856
	ds_read_b128 v[180:183], v52 offset:57888
	ds_read_b128 v[156:159], v52 offset:53312
	ds_read_b128 v[152:155], v52 offset:53344
	v_sub_f32_e32 v70, v70, v210
	v_add_u32_e32 v209, s41, v189
	v_mfma_f32_32x32x16_bf16 v[36:51], v[148:151], v[104:107], v[36:51]
	ds_read_b128 v[176:179], v52 offset:57920
	ds_read_b128 v[148:151], v52 offset:57952
	v_sub_f32_e32 v52, v84, v210
	v_exp_f32_e32 v211, v52
	v_sub_f32_e32 v52, v68, v210
	v_exp_f32_e32 v232, v52
	v_sub_f32_e32 v52, v85, v210
	v_exp_f32_e32 v233, v52
	v_mfma_f32_32x32x16_bf16 v[52:67], v[144:147], v[100:103], 0
	v_sub_f32_e32 v68, v69, v210
	v_exp_f32_e32 v235, v68
	v_sub_f32_e32 v84, v86, v210
	v_add_f32_e32 v68, v211, v232
	v_add_f32_e32 v68, 0, v68
	v_add_f32_e32 v69, v233, v235
	v_add_f32_e32 v68, v69, v68
	v_mfma_f32_32x32x16_bf16 v[52:67], v[172:175], v[104:107], v[52:67]
	v_exp_f32_e32 v173, v70
	v_sub_f32_e32 v70, v87, v210
	v_exp_f32_e32 v172, v84
	v_exp_f32_e32 v174, v70
	v_sub_f32_e32 v70, v71, v210
	v_exp_f32_e32 v175, v70
	v_add_f32_e32 v69, v172, v173
	v_add_f32_e32 v68, v69, v68
	v_mfma_f32_32x32x16_bf16 v[52:67], v[168:171], v[108:111], v[52:67]
	v_add_f32_e32 v69, v174, v175
	v_add_f32_e32 v168, v69, v68
	v_sub_f32_e32 v68, v88, v210
	v_exp_f32_e32 v71, v68
	v_sub_f32_e32 v68, v72, v210
	v_exp_f32_e32 v85, v68
	v_sub_f32_e32 v68, v89, v210
	v_exp_f32_e32 v70, v68
	v_sub_f32_e32 v68, v73, v210
	v_exp_f32_e32 v84, v68
	v_sub_f32_e32 v68, v90, v210
	v_exp_f32_e32 v73, v68
	v_sub_f32_e32 v68, v74, v210
	v_exp_f32_e32 v87, v68
	v_sub_f32_e32 v68, v91, v210
	v_exp_f32_e32 v72, v68
	v_sub_f32_e32 v68, v75, v210
	v_exp_f32_e32 v86, v68
	v_pk_add_f32 v[68:69], v[70:71], v[84:85]
	v_mfma_f32_32x32x16_bf16 v[36:51], v[140:143], v[108:111], v[36:51]
	v_add_f32_e32 v69, v69, v168
	v_add_f32_e32 v74, v68, v69
	v_add_f32_e64 v68, v72, v86
	v_add_f32_e64 v69, v73, v87
	ds_read_b128 v[132:135], v209
	ds_read_b128 v[128:131], v209 offset:32
	ds_read_b128 v[136:139], v209 offset:6656
	ds_read_b128 v[124:127], v209 offset:64
	v_add_f32_e32 v69, v69, v74
	v_add_f32_e32 v168, v68, v69
	v_sub_f32_e32 v68, v92, v210
	v_exp_f32_e32 v75, v68
	v_sub_f32_e32 v68, v76, v210
	v_exp_f32_e32 v89, v68
	v_sub_f32_e32 v68, v93, v210
	v_exp_f32_e32 v74, v68
	v_sub_f32_e32 v68, v77, v210
	v_exp_f32_e32 v88, v68
	v_sub_f32_e32 v68, v94, v210
	v_exp_f32_e32 v77, v68
	v_sub_f32_e32 v68, v78, v210
	s_waitcnt lgkmcnt(12)
	v_mfma_f32_32x32x16_bf16 v[36:51], v[220:223], v[112:115], v[36:51]
	v_exp_f32_e32 v91, v68
	v_sub_f32_e32 v68, v95, v210
	v_exp_f32_e32 v76, v68
	v_sub_f32_e32 v68, v79, v210
	v_exp_f32_e32 v90, v68
	v_pk_add_f32 v[68:69], v[74:75], v[88:89]
	ds_read_b128 v[144:147], v209 offset:6688
	ds_read_b128 v[140:143], v209 offset:6720
	v_mfma_f32_32x32x16_bf16 v[52:67], v[212:215], v[112:115], v[52:67]
	v_add_f32_e32 v69, v69, v168
	v_add_f32_e32 v78, v68, v69
	v_add_f32_e64 v68, v76, v90
	v_add_f32_e64 v69, v77, v91
	v_add_f32_e32 v69, v69, v78
	v_add_f32_e32 v168, v68, v69
	v_sub_f32_e32 v68, v96, v210
	v_mfma_f32_32x32x16_bf16 v[36:51], v[228:231], v[116:119], v[36:51]
	v_exp_f32_e32 v79, v68
	v_sub_f32_e32 v68, v80, v210
	v_exp_f32_e32 v93, v68
	v_sub_f32_e32 v68, v97, v210
	v_exp_f32_e32 v78, v68
	v_sub_f32_e32 v68, v81, v210
	v_exp_f32_e32 v92, v68
	v_mfma_f32_32x32x16_bf16 v[52:67], v[216:219], v[116:119], v[52:67]
	v_sub_f32_e32 v68, v98, v210
	v_exp_f32_e32 v95, v68
	v_sub_f32_e32 v68, v82, v210
	v_exp_f32_e32 v97, v68
	v_sub_f32_e32 v68, v99, v210
	v_exp_f32_e32 v94, v68
	v_sub_f32_e32 v68, v83, v210
	v_mfma_f32_32x32x16_bf16 v[36:51], v[238:241], v[120:123], v[36:51]
	v_exp_f32_e32 v96, v68
	v_pk_add_f32 v[68:69], v[78:79], v[92:93]
	s_nop 0
	v_add_f32_e32 v69, v69, v168
	v_add_f32_e32 v80, v68, v69
	v_pk_add_f32 v[68:69], v[94:95], v[96:97]
	v_mfma_f32_32x32x16_bf16 v[52:67], v[224:227], v[120:123], v[52:67]
	v_add_f32_e32 v69, v69, v80
	v_add_f32_e32 v68, v68, v69
	v_add_f32_e32 v209, v2, v68
	v_cvt_pk_bf16_f32 v68, v211, v233
	v_cvt_pk_bf16_f32 v69, v172, v174
	v_cvt_pk_bf16_f32 v70, v71, v70
	v_cvt_pk_bf16_f32 v71, v73, v72
	v_cvt_pk_bf16_f32 v80, v75, v74
	v_cvt_pk_bf16_f32 v81, v77, v76
	v_cvt_pk_bf16_f32 v82, v79, v78
	v_cvt_pk_bf16_f32 v83, v95, v94
	v_cvt_pk_bf16_f32 v76, v232, v235
	v_cvt_pk_bf16_f32 v77, v173, v175
	v_cvt_pk_bf16_f32 v78, v85, v84
	v_cvt_pk_bf16_f32 v79, v87, v86
	v_cvt_pk_bf16_f32 v72, v89, v88
	v_cvt_pk_bf16_f32 v73, v91, v90
	v_cvt_pk_bf16_f32 v74, v93, v92
	v_cvt_pk_bf16_f32 v75, v97, v96
	s_waitcnt vmcnt(3) lgkmcnt(0)
	s_barrier
	s_cmp_ge_u32 s42, s36
	s_cbranch_scc1 .LBB0_1011
	s_mov_b32 s14, s41
	s_mov_b32 s15, s38
	s_mov_b32 s41, s45
	s_mov_b32 s38, s44
	s_mov_b32 s44, s40
	s_mov_b32 s40, s43
	s_mov_b32 s46, s42
	s_branch .LBB0_999

; __global__ void __launch_bounds__(NWAVES * 64, 2) mk_fwd(Args args) {
	.amdhsa_kernel _Z6mk_fwd4Args
		.amdhsa_group_segment_fixed_size 0
		.amdhsa_private_segment_fixed_size 0
		.amdhsa_kernarg_size 528
		.amdhsa_user_sgpr_count 2
		.amdhsa_user_sgpr_dispatch_ptr 0
		.amdhsa_user_sgpr_queue_ptr 0
		.amdhsa_user_sgpr_kernarg_segment_ptr 1
		.amdhsa_user_sgpr_dispatch_id 0
		.amdhsa_user_sgpr_kernarg_preload_length 0
		.amdhsa_user_sgpr_kernarg_preload_offset 0
		.amdhsa_user_sgpr_private_segment_size 0
		.amdhsa_uses_dynamic_stack 0
		.amdhsa_enable_private_segment 0
		.amdhsa_system_sgpr_workgroup_id_x 1
		.amdhsa_system_sgpr_workgroup_id_y 0
		.amdhsa_system_sgpr_workgroup_id_z 0
		.amdhsa_system_sgpr_workgroup_info 0
		.amdhsa_system_vgpr_workitem_id 0
		.amdhsa_next_free_vgpr 255
		.amdhsa_next_free_sgpr 100
		.amdhsa_accum_offset 256
		.amdhsa_reserve_vcc 1
		.amdhsa_float_round_mode_32 0
		.amdhsa_float_round_mode_16_64 0
		.amdhsa_float_denorm_mode_32 3
		.amdhsa_float_denorm_mode_16_64 3
		.amdhsa_dx10_clamp 1
		.amdhsa_ieee_mode 1
		.amdhsa_fp16_overflow 0
		.amdhsa_tg_split 0
		.amdhsa_exception_fp_ieee_invalid_op 0
		.amdhsa_exception_fp_denorm_src 0
		.amdhsa_exception_fp_ieee_div_zero 0
		.amdhsa_exception_fp_ieee_overflow 0
		.amdhsa_exception_fp_ieee_underflow 0
		.amdhsa_exception_fp_ieee_inexact 0
		.amdhsa_exception_int_div_zero 0
	.end_amdhsa_kernel

; __global__ void __launch_bounds__(NWAVES * 64, 2) mk_fwd(Args args) {
amdhsa.kernels:
  - .agpr_count:     0
    .args:
      - .offset:         0
        .size:           272
        .value_kind:     by_value
      - .offset:         272
        .size:           4
        .value_kind:     hidden_block_count_x
      - .offset:         276
        .size:           4
        .value_kind:     hidden_block_count_y
      - .offset:         280
        .size:           4
        .value_kind:     hidden_block_count_z
      - .offset:         284
        .size:           2
        .value_kind:     hidden_group_size_x
      - .offset:         286
        .size:           2
        .value_kind:     hidden_group_size_y
      - .offset:         288
        .size:           2
        .value_kind:     hidden_group_size_z
      - .offset:         290
        .size:           2
        .value_kind:     hidden_remainder_x
      - .offset:         292
        .size:           2
        .value_kind:     hidden_remainder_y
      - .offset:         294
        .size:           2
        .value_kind:     hidden_remainder_z
      - .offset:         312
        .size:           8
        .value_kind:     hidden_global_offset_x
      - .offset:         320
        .size:           8
        .value_kind:     hidden_global_offset_y
      - .offset:         328
        .size:           8
        .value_kind:     hidden_global_offset_z
      - .offset:         336
        .size:           2
        .value_kind:     hidden_grid_dims
      - .offset:         392
        .size:           4
        .value_kind:     hidden_dynamic_lds_size
    .group_segment_fixed_size: 0
    .kernarg_segment_align: 8
    .kernarg_segment_size: 528
    .language:       OpenCL C
    .language_version:
      - 2
      - 0
    .max_flat_workgroup_size: 512
    .name:           _Z6mk_fwd4Args
    .private_segment_fixed_size: 0
    .sgpr_count:     106
    .sgpr_spill_count: 28
    .symbol:         _Z6mk_fwd4Args.kd
    .uniform_work_group_size: 1
    .uses_dynamic_stack: false
    .vgpr_count:     255
    .vgpr_spill_count: 0
    .wavefront_size: 64
